# SB: all K/V fragment LDS reads issued up front with counted waits, Q-load wait moved to first-unit path; stream-update loops: counted vmcnt keeps next row loads in flight
# speedup vs baseline: 1.0236x; 1.0030x over previous
.LBB0_632:
	v_add_u32_e32 v52, s14, v54
	v_cmp_gt_i32_e64 s[10:11], s81, v52
	v_ashrrev_i32_e32 v53, 31, v52
	s_and_saveexec_b64 s[6:7], s[10:11]
	s_cbranch_execz .LBB0_636
	v_lshlrev_b64 v[40:41], 11, v[52:53]
	v_lshl_or_b32 v40, v56, 1, v40
	v_lshl_add_u64 v[36:37], s[52:53], 0, v[40:41]
	v_lshl_add_u64 v[40:41], s[60:61], 0, v[40:41]
	global_load_dwordx4 v[32:35], v[36:37], off
	s_nop 0
	global_load_dwordx4 v[36:39], v[36:37], off offset:1024
	s_nop 0
	global_load_dwordx4 v[44:47], v[40:41], off
	s_nop 0
	global_load_dwordx4 v[40:43], v[40:41], off offset:1024
	v_mov_b32_e32 v64, 0
	s_and_saveexec_b64 s[12:13], vcc
	s_cbranch_execz .LBB0_635
	v_lshlrev_b64 v[64:65], 6, v[52:53]
	v_lshl_add_u64 v[64:65], v[50:51], 0, v[64:65]
	global_load_dword v64, v[64:65], off
	s_or_b64 exec, exec, s[12:13]
	s_or_b64 exec, exec, s[6:7]
	s_waitcnt vmcnt(5) lgkmcnt(0)
	s_branch .Le0_p1

.Le0_p1:
	ds_bpermute_b32 v55, v58, v57
	v_lshlrev_b32_e32 v70, 16, v24
	v_and_b32_e32 v71, 0xffff0000, v24
	v_lshlrev_b32_e32 v68, 16, v16
	v_and_b32_e32 v69, 0xffff0000, v16
	s_waitcnt lgkmcnt(0)
	v_add_f32_e32 v55, v57, v55
	ds_bpermute_b32 v65, v59, v55
	v_lshlrev_b32_e32 v72, 16, v25
	v_and_b32_e32 v73, 0xffff0000, v25
	v_lshlrev_b32_e32 v74, 16, v26
	v_and_b32_e32 v75, 0xffff0000, v26
	s_waitcnt lgkmcnt(0)
	v_add_f32_e32 v55, v55, v65
	ds_bpermute_b32 v65, v60, v55
	v_lshlrev_b32_e32 v76, 16, v27
	v_and_b32_e32 v77, 0xffff0000, v27
	v_lshlrev_b32_e32 v78, 16, v28
	v_and_b32_e32 v79, 0xffff0000, v28
	s_waitcnt lgkmcnt(0)
	v_add_f32_e32 v55, v55, v65
	ds_bpermute_b32 v65, v61, v55
	v_lshlrev_b32_e32 v80, 16, v29
	v_and_b32_e32 v81, 0xffff0000, v29
	v_lshlrev_b32_e32 v82, 16, v30
	v_and_b32_e32 v83, 0xffff0000, v30
	s_waitcnt lgkmcnt(0)
	v_add_f32_e32 v55, v55, v65
	ds_bpermute_b32 v65, v62, v55
	v_lshlrev_b32_e32 v84, 16, v31
	v_and_b32_e32 v85, 0xffff0000, v31
	s_waitcnt lgkmcnt(0)
	v_add_f32_e32 v55, v55, v65
	ds_bpermute_b32 v65, v63, v55
	s_waitcnt lgkmcnt(0)
	v_add_f32_e32 v55, v55, v65
	v_fmamk_f32 v55, v55, 0x3a800000, v156
	v_cmp_gt_f32_e64 s[12:13], s28, v55
	v_mul_f32_e32 v65, 0x4b800000, v55
	s_nop 0
	v_cndmask_b32_e64 v55, v55, v65, s[12:13]
	v_rsq_f32_e32 v55, v55
	s_nop 0
	v_mul_f32_e32 v65, 0x45800000, v55
	v_cndmask_b32_e64 v66, v55, v65, s[12:13]
	v_pk_mul_f32 v[70:71], v[66:67], v[70:71] op_sel_hi:[0,1]
	v_pk_fma_f32 v[70:71], v[4:5], v[70:71], v[68:69]
	v_lshlrev_b32_e32 v68, 16, v17
	v_and_b32_e32 v69, 0xffff0000, v17
	v_pk_mul_f32 v[72:73], v[66:67], v[72:73] op_sel_hi:[0,1]
	v_pk_fma_f32 v[72:73], v[6:7], v[72:73], v[68:69]
	v_lshlrev_b32_e32 v68, 16, v18
	v_and_b32_e32 v69, 0xffff0000, v18
	v_pk_mul_f32 v[74:75], v[66:67], v[74:75] op_sel_hi:[0,1]
	v_pk_fma_f32 v[74:75], v[0:1], v[74:75], v[68:69]
	v_lshlrev_b32_e32 v68, 16, v19
	v_and_b32_e32 v69, 0xffff0000, v19
	v_pk_mul_f32 v[76:77], v[66:67], v[76:77] op_sel_hi:[0,1]
	v_pk_fma_f32 v[76:77], v[2:3], v[76:77], v[68:69]
	v_lshlrev_b32_e32 v68, 16, v20
	v_and_b32_e32 v69, 0xffff0000, v20
	v_pk_mul_f32 v[78:79], v[66:67], v[78:79] op_sel_hi:[0,1]
	v_pk_fma_f32 v[78:79], v[12:13], v[78:79], v[68:69]
	v_lshlrev_b32_e32 v68, 16, v21
	v_and_b32_e32 v69, 0xffff0000, v21
	v_pk_mul_f32 v[80:81], v[66:67], v[80:81] op_sel_hi:[0,1]
	v_pk_fma_f32 v[80:81], v[14:15], v[80:81], v[68:69]
	v_lshlrev_b32_e32 v68, 16, v22
	v_and_b32_e32 v69, 0xffff0000, v22
	v_pk_mul_f32 v[82:83], v[66:67], v[82:83] op_sel_hi:[0,1]
	v_pk_fma_f32 v[82:83], v[8:9], v[82:83], v[68:69]
	v_lshlrev_b32_e32 v68, 16, v23
	v_and_b32_e32 v69, 0xffff0000, v23
	v_pk_mul_f32 v[66:67], v[66:67], v[84:85] op_sel_hi:[0,1]
	v_pk_fma_f32 v[84:85], v[10:11], v[66:67], v[68:69]
	v_cvt_pk_bf16_f32 v66, v70, v71
	v_pk_mul_f32 v[70:71], v[70:71], v[70:71]
	v_cvt_pk_bf16_f32 v67, v72, v73
	v_pk_mul_f32 v[72:73], v[72:73], v[72:73]
	v_add_f32_e32 v65, v70, v71
	v_add_f32_e32 v65, v72, v65
	v_cvt_pk_bf16_f32 v68, v74, v75
	v_pk_mul_f32 v[74:75], v[74:75], v[74:75]
	v_add_f32_e32 v65, v73, v65
	v_ashrrev_i32_e32 v55, 31, v54
	v_add_f32_e32 v65, v74, v65
	v_lshlrev_b64 v[86:87], 11, v[54:55]
	v_cvt_pk_bf16_f32 v69, v76, v77
	v_pk_mul_f32 v[76:77], v[76:77], v[76:77]
	v_add_f32_e32 v65, v75, v65
	v_lshl_add_u64 v[86:87], v[48:49], 0, v[86:87]
	v_add_f32_e32 v65, v76, v65
	global_store_dwordx4 v[86:87], v[66:69], off
	v_add_f32_e32 v65, v77, v65
	s_nop 0
	v_cvt_pk_bf16_f32 v66, v78, v79
	v_pk_mul_f32 v[78:79], v[78:79], v[78:79]
	v_cvt_pk_bf16_f32 v67, v80, v81
	v_add_f32_e32 v65, v78, v65
	v_pk_mul_f32 v[80:81], v[80:81], v[80:81]
	v_add_f32_e32 v65, v79, v65
	v_add_f32_e32 v65, v80, v65
	v_cvt_pk_bf16_f32 v68, v82, v83
	v_pk_mul_f32 v[82:83], v[82:83], v[82:83]
	v_add_f32_e32 v65, v81, v65
	v_add_f32_e32 v65, v82, v65
	v_cvt_pk_bf16_f32 v69, v84, v85
	v_pk_mul_f32 v[84:85], v[84:85], v[84:85]
	v_add_f32_e32 v65, v83, v65
	v_add_f32_e32 v65, v84, v65
	v_add_f32_e32 v65, v85, v65
	global_store_dwordx4 v[86:87], v[66:69], off offset:1024
	ds_bpermute_b32 v66, v58, v65
	s_waitcnt lgkmcnt(0)
	v_add_f32_e32 v65, v65, v66
	ds_bpermute_b32 v66, v59, v65
	s_waitcnt lgkmcnt(0)
	v_add_f32_e32 v65, v65, v66
	ds_bpermute_b32 v66, v60, v65
	s_waitcnt lgkmcnt(0)
	v_add_f32_e32 v65, v65, v66
	ds_bpermute_b32 v66, v61, v65
	s_waitcnt lgkmcnt(0)
	v_add_f32_e32 v65, v65, v66
	ds_bpermute_b32 v66, v62, v65
	s_waitcnt lgkmcnt(0)
	v_add_f32_e32 v65, v65, v66
	ds_bpermute_b32 v66, v63, v65
	s_and_saveexec_b64 s[6:7], s[8:9]
	s_cbranch_execz .LBB0_638
	s_waitcnt lgkmcnt(0)
	v_add_f32_e32 v65, v65, v66
	v_fmamk_f32 v65, v65, 0x3a800000, v156
	v_mul_f32_e32 v66, 0x4b800000, v65
	v_cmp_gt_f32_e64 s[12:13], s28, v65
	s_nop 1
	v_cndmask_b32_e64 v65, v65, v66, s[12:13]
	v_rsq_f32_e32 v65, v65
	s_nop 0
	v_mul_f32_e32 v66, 0x45800000, v65
	v_cndmask_b32_e64 v65, v65, v66, s[12:13]
	v_lshl_add_u64 v[66:67], v[54:55], 2, s[38:39]
	global_store_dword v[66:67], v65, off
.LBB0_638:
	s_or_b64 exec, exec, s[6:7]
	s_and_saveexec_b64 s[12:13], s[10:11]
	s_cbranch_execz .LBB0_631
	v_add_u32_e32 v54, s18, v54
	v_cmp_gt_i32_e64 s[10:11], s81, v54
	s_and_saveexec_b64 s[6:7], s[10:11]
	s_cbranch_execz .LBB0_643
	v_ashrrev_i32_e32 v55, 31, v54
	v_lshlrev_b64 v[24:25], 11, v[54:55]
	v_lshl_or_b32 v24, v56, 1, v24
	v_lshl_add_u64 v[20:21], s[52:53], 0, v[24:25]
	v_lshl_add_u64 v[28:29], s[60:61], 0, v[24:25]
	global_load_dwordx4 v[16:19], v[20:21], off
	s_nop 0
	global_load_dwordx4 v[20:23], v[20:21], off offset:1024
	s_nop 0
	global_load_dwordx4 v[24:27], v[28:29], off
	s_nop 0
	global_load_dwordx4 v[28:31], v[28:29], off offset:1024
	v_mov_b32_e32 v57, 0
	s_and_saveexec_b64 s[10:11], vcc
	s_cbranch_execz .LBB0_642
	v_lshlrev_b64 v[54:55], 6, v[54:55]
	v_lshl_add_u64 v[54:55], v[50:51], 0, v[54:55]
	global_load_dword v57, v[54:55], off
	s_or_b64 exec, exec, s[10:11]
	s_or_b64 exec, exec, s[6:7]
	s_waitcnt vmcnt(5)
	s_branch .Le0_p2

.Le0_p2:
	ds_bpermute_b32 v54, v58, v64
	v_lshlrev_b32_e32 v68, 16, v44
	v_and_b32_e32 v69, 0xffff0000, v44
	s_waitcnt lgkmcnt(1)
	v_lshlrev_b32_e32 v66, 16, v32
	v_and_b32_e32 v67, 0xffff0000, v32
	s_waitcnt lgkmcnt(0)
	v_add_f32_e32 v54, v64, v54
	ds_bpermute_b32 v55, v59, v54
	v_lshlrev_b64 v[84:85], 11, v[52:53]
	v_lshl_add_u64 v[84:85], v[48:49], 0, v[84:85]
	s_waitcnt lgkmcnt(0)
	v_add_f32_e32 v54, v54, v55
	ds_bpermute_b32 v55, v60, v54
	s_waitcnt lgkmcnt(0)
	v_add_f32_e32 v54, v54, v55
	ds_bpermute_b32 v55, v61, v54
	s_waitcnt lgkmcnt(0)
	v_add_f32_e32 v54, v54, v55
	ds_bpermute_b32 v55, v62, v54
	s_waitcnt lgkmcnt(0)
	v_add_f32_e32 v54, v54, v55
	ds_bpermute_b32 v55, v63, v54
	s_waitcnt lgkmcnt(0)
	v_add_f32_e32 v54, v54, v55
	v_fmamk_f32 v54, v54, 0x3a800000, v156
	v_cmp_gt_f32_e64 s[10:11], s28, v54
	v_mul_f32_e32 v55, 0x4b800000, v54
	s_nop 0
	v_cndmask_b32_e64 v54, v54, v55, s[10:11]
	v_rsq_f32_e32 v54, v54
	s_nop 0
	v_mul_f32_e32 v55, 0x45800000, v54
	v_cndmask_b32_e64 v54, v54, v55, s[10:11]
	v_pk_mul_f32 v[68:69], v[54:55], v[68:69] op_sel_hi:[0,1]
	v_pk_fma_f32 v[70:71], v[4:5], v[68:69], v[66:67]
	v_lshlrev_b32_e32 v68, 16, v45
	v_and_b32_e32 v69, 0xffff0000, v45
	v_lshlrev_b32_e32 v66, 16, v33
	v_and_b32_e32 v67, 0xffff0000, v33
	v_pk_mul_f32 v[68:69], v[54:55], v[68:69] op_sel_hi:[0,1]
	v_pk_fma_f32 v[72:73], v[6:7], v[68:69], v[66:67]
	v_lshlrev_b32_e32 v68, 16, v46
	v_and_b32_e32 v69, 0xffff0000, v46
	v_lshlrev_b32_e32 v66, 16, v34
	v_and_b32_e32 v67, 0xffff0000, v34
	v_pk_mul_f32 v[68:69], v[54:55], v[68:69] op_sel_hi:[0,1]
	v_pk_fma_f32 v[74:75], v[0:1], v[68:69], v[66:67]
	v_lshlrev_b32_e32 v68, 16, v47
	v_and_b32_e32 v69, 0xffff0000, v47
	v_lshlrev_b32_e32 v66, 16, v35
	v_and_b32_e32 v67, 0xffff0000, v35
	v_pk_mul_f32 v[68:69], v[54:55], v[68:69] op_sel_hi:[0,1]
	v_pk_fma_f32 v[76:77], v[2:3], v[68:69], v[66:67]
	v_lshlrev_b32_e32 v68, 16, v40
	v_and_b32_e32 v69, 0xffff0000, v40
	v_lshlrev_b32_e32 v66, 16, v36
	v_and_b32_e32 v67, 0xffff0000, v36
	v_pk_mul_f32 v[68:69], v[54:55], v[68:69] op_sel_hi:[0,1]
	v_pk_fma_f32 v[78:79], v[12:13], v[68:69], v[66:67]
	v_lshlrev_b32_e32 v68, 16, v41
	v_and_b32_e32 v69, 0xffff0000, v41
	v_lshlrev_b32_e32 v66, 16, v37
	v_and_b32_e32 v67, 0xffff0000, v37
	v_pk_mul_f32 v[68:69], v[54:55], v[68:69] op_sel_hi:[0,1]
	v_pk_fma_f32 v[80:81], v[14:15], v[68:69], v[66:67]
	v_lshlrev_b32_e32 v68, 16, v42
	v_and_b32_e32 v69, 0xffff0000, v42
	v_lshlrev_b32_e32 v66, 16, v38
	v_and_b32_e32 v67, 0xffff0000, v38
	v_pk_mul_f32 v[68:69], v[54:55], v[68:69] op_sel_hi:[0,1]
	v_pk_fma_f32 v[82:83], v[8:9], v[68:69], v[66:67]
	v_lshlrev_b32_e32 v68, 16, v43
	v_and_b32_e32 v69, 0xffff0000, v43
	v_lshlrev_b32_e32 v66, 16, v39
	v_and_b32_e32 v67, 0xffff0000, v39
	v_pk_mul_f32 v[54:55], v[54:55], v[68:69] op_sel_hi:[0,1]
	v_pk_fma_f32 v[54:55], v[10:11], v[54:55], v[66:67]
	v_cvt_pk_bf16_f32 v66, v70, v71
	v_pk_mul_f32 v[70:71], v[70:71], v[70:71]
	v_cvt_pk_bf16_f32 v67, v72, v73
	v_pk_mul_f32 v[72:73], v[72:73], v[72:73]
	v_add_f32_e32 v65, v70, v71
	v_add_f32_e32 v65, v72, v65
	v_cvt_pk_bf16_f32 v68, v74, v75
	v_pk_mul_f32 v[74:75], v[74:75], v[74:75]
	v_add_f32_e32 v65, v73, v65
	v_add_f32_e32 v65, v74, v65
	v_cvt_pk_bf16_f32 v69, v76, v77
	v_pk_mul_f32 v[76:77], v[76:77], v[76:77]
	v_add_f32_e32 v65, v75, v65
	v_add_f32_e32 v65, v76, v65
	global_store_dwordx4 v[84:85], v[66:69], off
	v_add_f32_e32 v65, v77, v65
	s_nop 0
	v_cvt_pk_bf16_f32 v66, v78, v79
	v_pk_mul_f32 v[78:79], v[78:79], v[78:79]
	v_cvt_pk_bf16_f32 v67, v80, v81
	v_add_f32_e32 v65, v78, v65
	v_pk_mul_f32 v[80:81], v[80:81], v[80:81]
	v_add_f32_e32 v65, v79, v65
	v_add_f32_e32 v65, v80, v65
	v_cvt_pk_bf16_f32 v68, v82, v83
	v_pk_mul_f32 v[82:83], v[82:83], v[82:83]
	v_add_f32_e32 v65, v81, v65
	v_add_f32_e32 v65, v82, v65
	v_cvt_pk_bf16_f32 v69, v54, v55
	v_pk_mul_f32 v[54:55], v[54:55], v[54:55]
	v_add_f32_e32 v65, v83, v65
	v_add_f32_e32 v54, v54, v65
	v_add_f32_e32 v54, v55, v54
	ds_bpermute_b32 v55, v58, v54
	global_store_dwordx4 v[84:85], v[66:69], off offset:1024
	s_waitcnt lgkmcnt(0)
	v_add_f32_e32 v54, v54, v55
	ds_bpermute_b32 v55, v59, v54
	s_waitcnt lgkmcnt(0)
	v_add_f32_e32 v54, v54, v55
	ds_bpermute_b32 v55, v60, v54
	s_waitcnt lgkmcnt(0)
	v_add_f32_e32 v54, v54, v55
	ds_bpermute_b32 v55, v61, v54
	s_waitcnt lgkmcnt(0)
	v_add_f32_e32 v54, v54, v55
	ds_bpermute_b32 v55, v62, v54
	s_waitcnt lgkmcnt(0)
	v_add_f32_e32 v54, v54, v55
	ds_bpermute_b32 v55, v63, v54
	s_and_saveexec_b64 s[6:7], s[8:9]
	s_cbranch_execz .LBB0_630
	s_waitcnt lgkmcnt(0)
	v_add_f32_e32 v54, v54, v55
	v_fmamk_f32 v54, v54, 0x3a800000, v156
	v_mul_f32_e32 v55, 0x4b800000, v54
	v_cmp_gt_f32_e64 s[10:11], s28, v54
	s_nop 1
	v_cndmask_b32_e64 v54, v54, v55, s[10:11]
	v_rsq_f32_e32 v54, v54
	s_nop 0
	v_mul_f32_e32 v55, 0x45800000, v54
	v_cndmask_b32_e64 v65, v54, v55, s[10:11]
	v_lshl_add_u64 v[54:55], v[52:53], 2, s[38:39]
	global_store_dword v[54:55], v65, off
	s_branch .LBB0_630

.LBB0_719:
	v_add_u32_e32 v68, s14, v70
	v_cmp_gt_i32_e64 s[10:11], s81, v68
	v_ashrrev_i32_e32 v69, 31, v68
	s_and_saveexec_b64 s[6:7], s[10:11]
	s_cbranch_execz .LBB0_723
	s_load_dwordx2 s[12:13], s[0:1], 0x0
	v_lshlrev_b64 v[56:57], 10, v[68:69]
	v_or_b32_e32 v56, v56, v72
	v_mov_b32_e32 v80, 0
	s_waitcnt lgkmcnt(0)
	v_lshl_add_u64 v[48:49], v[56:57], 2, s[12:13]
	global_load_dwordx4 v[44:47], v[48:49], off offset:16
	global_load_dwordx4 v[52:55], v[48:49], off
	global_load_dwordx4 v[40:43], v[48:49], off offset:2064
	s_nop 0
	global_load_dwordx4 v[48:51], v[48:49], off offset:2048
	v_lshl_add_u64 v[56:57], v[56:57], 1, s[60:61]
	global_load_dwordx4 v[60:63], v[56:57], off
	s_nop 0
	global_load_dwordx4 v[56:59], v[56:57], off offset:1024
	s_and_saveexec_b64 s[12:13], vcc
	s_cbranch_execz .LBB0_722
	v_lshlrev_b64 v[80:81], 6, v[68:69]
	v_lshl_add_u64 v[80:81], v[66:67], 0, v[80:81]
	global_load_dword v80, v[80:81], off
	s_or_b64 exec, exec, s[12:13]
	s_or_b64 exec, exec, s[6:7]
	s_waitcnt vmcnt(7) lgkmcnt(0)
	s_branch .Le0_p3

.Le0_p3:
	ds_bpermute_b32 v71, v74, v73
	v_lshlrev_b32_e32 v84, 16, v32
	v_and_b32_e32 v85, 0xffff0000, v32
	s_waitcnt lgkmcnt(0)
	v_add_f32_e32 v71, v73, v71
	ds_bpermute_b32 v81, v75, v71
	s_waitcnt lgkmcnt(0)
	v_add_f32_e32 v71, v71, v81
	ds_bpermute_b32 v81, v76, v71
	s_waitcnt lgkmcnt(0)
	v_add_f32_e32 v71, v71, v81
	ds_bpermute_b32 v81, v77, v71
	s_waitcnt lgkmcnt(0)
	v_add_f32_e32 v71, v71, v81
	ds_bpermute_b32 v81, v78, v71
	s_waitcnt lgkmcnt(0)
	v_add_f32_e32 v71, v71, v81
	ds_bpermute_b32 v81, v79, v71
	s_waitcnt lgkmcnt(0)
	v_add_f32_e32 v71, v71, v81
	v_fmamk_f32 v71, v71, 0x3a800000, v156
	v_cmp_gt_f32_e64 s[12:13], s28, v71
	v_mul_f32_e32 v81, 0x4b800000, v71
	s_nop 0
	v_cndmask_b32_e64 v71, v71, v81, s[12:13]
	v_rsq_f32_e32 v71, v71
	s_nop 0
	v_mul_f32_e32 v81, 0x45800000, v71
	v_cndmask_b32_e64 v82, v71, v81, s[12:13]
	v_pk_mul_f32 v[84:85], v[82:83], v[84:85] op_sel_hi:[0,1]
	v_pk_fma_f32 v[86:87], v[4:5], v[84:85], v[20:21]
	v_lshlrev_b32_e32 v84, 16, v33
	v_and_b32_e32 v85, 0xffff0000, v33
	v_pk_mul_f32 v[84:85], v[82:83], v[84:85] op_sel_hi:[0,1]
	v_pk_fma_f32 v[88:89], v[6:7], v[84:85], v[22:23]
	v_lshlrev_b32_e32 v84, 16, v34
	v_and_b32_e32 v85, 0xffff0000, v34
	v_pk_mul_f32 v[84:85], v[82:83], v[84:85] op_sel_hi:[0,1]
	v_pk_fma_f32 v[90:91], v[0:1], v[84:85], v[16:17]
	v_lshlrev_b32_e32 v84, 16, v35
	v_and_b32_e32 v85, 0xffff0000, v35
	v_pk_mul_f32 v[84:85], v[82:83], v[84:85] op_sel_hi:[0,1]
	v_pk_fma_f32 v[92:93], v[2:3], v[84:85], v[18:19]
	v_lshlrev_b32_e32 v84, 16, v36
	v_and_b32_e32 v85, 0xffff0000, v36
	v_pk_mul_f32 v[84:85], v[82:83], v[84:85] op_sel_hi:[0,1]
	v_pk_fma_f32 v[94:95], v[12:13], v[84:85], v[28:29]
	v_lshlrev_b32_e32 v84, 16, v37
	v_and_b32_e32 v85, 0xffff0000, v37
	v_pk_mul_f32 v[84:85], v[82:83], v[84:85] op_sel_hi:[0,1]
	v_pk_fma_f32 v[96:97], v[14:15], v[84:85], v[30:31]
	v_lshlrev_b32_e32 v84, 16, v38
	v_and_b32_e32 v85, 0xffff0000, v38
	v_pk_mul_f32 v[84:85], v[82:83], v[84:85] op_sel_hi:[0,1]
	v_pk_fma_f32 v[98:99], v[8:9], v[84:85], v[24:25]
	v_lshlrev_b32_e32 v84, 16, v39
	v_and_b32_e32 v85, 0xffff0000, v39
	v_pk_mul_f32 v[82:83], v[82:83], v[84:85] op_sel_hi:[0,1]
	v_pk_fma_f32 v[100:101], v[10:11], v[82:83], v[26:27]
	v_cvt_pk_bf16_f32 v82, v86, v87
	v_pk_mul_f32 v[86:87], v[86:87], v[86:87]
	v_cvt_pk_bf16_f32 v83, v88, v89
	v_pk_mul_f32 v[88:89], v[88:89], v[88:89]
	v_add_f32_e32 v81, v86, v87
	v_add_f32_e32 v81, v88, v81
	v_cvt_pk_bf16_f32 v84, v90, v91
	v_pk_mul_f32 v[90:91], v[90:91], v[90:91]
	v_add_f32_e32 v81, v89, v81
	v_ashrrev_i32_e32 v71, 31, v70
	v_add_f32_e32 v81, v90, v81
	v_lshlrev_b64 v[102:103], 11, v[70:71]
	v_cvt_pk_bf16_f32 v85, v92, v93
	v_pk_mul_f32 v[92:93], v[92:93], v[92:93]
	v_add_f32_e32 v81, v91, v81
	v_lshl_add_u64 v[102:103], v[64:65], 0, v[102:103]
	v_add_f32_e32 v81, v92, v81
	global_store_dwordx4 v[102:103], v[82:85], off
	v_add_f32_e32 v81, v93, v81
	s_nop 0
	v_cvt_pk_bf16_f32 v82, v94, v95
	v_pk_mul_f32 v[94:95], v[94:95], v[94:95]
	v_cvt_pk_bf16_f32 v83, v96, v97
	v_add_f32_e32 v81, v94, v81
	v_pk_mul_f32 v[96:97], v[96:97], v[96:97]
	v_add_f32_e32 v81, v95, v81
	v_add_f32_e32 v81, v96, v81
	v_cvt_pk_bf16_f32 v84, v98, v99
	v_pk_mul_f32 v[98:99], v[98:99], v[98:99]
	v_add_f32_e32 v81, v97, v81
	v_add_f32_e32 v81, v98, v81
	v_cvt_pk_bf16_f32 v85, v100, v101
	v_pk_mul_f32 v[100:101], v[100:101], v[100:101]
	v_add_f32_e32 v81, v99, v81
	v_add_f32_e32 v81, v100, v81
	v_add_f32_e32 v81, v101, v81
	global_store_dwordx4 v[102:103], v[82:85], off offset:1024
	ds_bpermute_b32 v82, v74, v81
	s_waitcnt lgkmcnt(0)
	v_add_f32_e32 v81, v81, v82
	ds_bpermute_b32 v82, v75, v81
	s_waitcnt lgkmcnt(0)
	v_add_f32_e32 v81, v81, v82
	ds_bpermute_b32 v82, v76, v81
	s_waitcnt lgkmcnt(0)
	v_add_f32_e32 v81, v81, v82
	ds_bpermute_b32 v82, v77, v81
	s_waitcnt lgkmcnt(0)
	v_add_f32_e32 v81, v81, v82
	ds_bpermute_b32 v82, v78, v81
	s_waitcnt lgkmcnt(0)
	v_add_f32_e32 v81, v81, v82
	ds_bpermute_b32 v82, v79, v81
	s_and_saveexec_b64 s[6:7], s[8:9]
	s_cbranch_execz .LBB0_725
	s_waitcnt lgkmcnt(0)
	v_add_f32_e32 v81, v81, v82
	v_fmamk_f32 v81, v81, 0x3a800000, v156
	v_mul_f32_e32 v82, 0x4b800000, v81
	v_cmp_gt_f32_e64 s[12:13], s28, v81
	s_nop 1
	v_cndmask_b32_e64 v81, v81, v82, s[12:13]
	v_rsq_f32_e32 v81, v81
	s_nop 0
	v_mul_f32_e32 v82, 0x45800000, v81
	v_cndmask_b32_e64 v81, v81, v82, s[12:13]
	v_lshl_add_u64 v[82:83], v[70:71], 2, s[38:39]
	global_store_dword v[82:83], v81, off
.LBB0_725:
	s_or_b64 exec, exec, s[6:7]
	s_and_saveexec_b64 s[12:13], s[10:11]
	s_cbranch_execz .LBB0_718
	v_add_u32_e32 v70, s18, v70
	v_cmp_gt_i32_e64 s[10:11], s81, v70
	s_and_saveexec_b64 s[6:7], s[10:11]
	s_cbranch_execz .LBB0_730
	s_load_dwordx2 s[10:11], s[0:1], 0x0
	v_ashrrev_i32_e32 v71, 31, v70
	v_lshlrev_b64 v[32:33], 10, v[70:71]
	v_or_b32_e32 v32, v32, v72
	v_lshl_add_u64 v[36:37], v[32:33], 1, s[60:61]
	s_waitcnt lgkmcnt(0)
	v_lshl_add_u64 v[28:29], v[32:33], 2, s[10:11]
	global_load_dwordx4 v[16:19], v[28:29], off offset:16
	global_load_dwordx4 v[20:23], v[28:29], off
	global_load_dwordx4 v[24:27], v[28:29], off offset:2064
	s_nop 0
	global_load_dwordx4 v[28:31], v[28:29], off offset:2048
	s_nop 0
	global_load_dwordx4 v[32:35], v[36:37], off
	s_nop 0
	global_load_dwordx4 v[36:39], v[36:37], off offset:1024
	v_mov_b32_e32 v73, 0
	s_and_saveexec_b64 s[10:11], vcc
	s_cbranch_execz .LBB0_729
	v_lshlrev_b64 v[70:71], 6, v[70:71]
	v_lshl_add_u64 v[70:71], v[66:67], 0, v[70:71]
	global_load_dword v73, v[70:71], off
	s_or_b64 exec, exec, s[10:11]
	s_or_b64 exec, exec, s[6:7]
	s_waitcnt vmcnt(7)
	s_branch .Le0_p4

.Le0_p4:
	ds_bpermute_b32 v70, v74, v80
	s_waitcnt lgkmcnt(1)
	v_lshlrev_b32_e32 v82, 16, v60
	v_and_b32_e32 v83, 0xffff0000, v60
	v_lshlrev_b64 v[100:101], 11, v[68:69]
	v_lshl_add_u64 v[100:101], v[64:65], 0, v[100:101]
	s_waitcnt lgkmcnt(0)
	v_add_f32_e32 v70, v80, v70
	ds_bpermute_b32 v71, v75, v70
	s_waitcnt lgkmcnt(0)
	v_add_f32_e32 v70, v70, v71
	ds_bpermute_b32 v71, v76, v70
	s_waitcnt lgkmcnt(0)
	v_add_f32_e32 v70, v70, v71
	ds_bpermute_b32 v71, v77, v70
	s_waitcnt lgkmcnt(0)
	v_add_f32_e32 v70, v70, v71
	ds_bpermute_b32 v71, v78, v70
	s_waitcnt lgkmcnt(0)
	v_add_f32_e32 v70, v70, v71
	ds_bpermute_b32 v71, v79, v70
	s_waitcnt lgkmcnt(0)
	v_add_f32_e32 v70, v70, v71
	v_fmamk_f32 v70, v70, 0x3a800000, v156
	v_cmp_gt_f32_e64 s[10:11], s28, v70
	v_mul_f32_e32 v71, 0x4b800000, v70
	s_nop 0
	v_cndmask_b32_e64 v70, v70, v71, s[10:11]
	v_rsq_f32_e32 v70, v70
	s_nop 0
	v_mul_f32_e32 v71, 0x45800000, v70
	v_cndmask_b32_e64 v70, v70, v71, s[10:11]
	v_pk_mul_f32 v[82:83], v[70:71], v[82:83] op_sel_hi:[0,1]
	v_pk_fma_f32 v[86:87], v[4:5], v[82:83], v[52:53]
	v_lshlrev_b32_e32 v82, 16, v61
	v_and_b32_e32 v83, 0xffff0000, v61
	v_pk_mul_f32 v[82:83], v[70:71], v[82:83] op_sel_hi:[0,1]
	v_pk_fma_f32 v[88:89], v[6:7], v[82:83], v[54:55]
	v_lshlrev_b32_e32 v82, 16, v62
	v_and_b32_e32 v83, 0xffff0000, v62
	v_pk_mul_f32 v[82:83], v[70:71], v[82:83] op_sel_hi:[0,1]
	v_pk_fma_f32 v[90:91], v[0:1], v[82:83], v[44:45]
	v_lshlrev_b32_e32 v82, 16, v63
	v_and_b32_e32 v83, 0xffff0000, v63
	v_pk_mul_f32 v[82:83], v[70:71], v[82:83] op_sel_hi:[0,1]
	v_pk_fma_f32 v[92:93], v[2:3], v[82:83], v[46:47]
	v_lshlrev_b32_e32 v82, 16, v56
	v_and_b32_e32 v83, 0xffff0000, v56
	v_pk_mul_f32 v[82:83], v[70:71], v[82:83] op_sel_hi:[0,1]
	v_pk_fma_f32 v[94:95], v[12:13], v[82:83], v[48:49]
	v_lshlrev_b32_e32 v82, 16, v57
	v_and_b32_e32 v83, 0xffff0000, v57
	v_pk_mul_f32 v[82:83], v[70:71], v[82:83] op_sel_hi:[0,1]
	v_pk_fma_f32 v[96:97], v[14:15], v[82:83], v[50:51]
	v_lshlrev_b32_e32 v82, 16, v58
	v_and_b32_e32 v83, 0xffff0000, v58
	v_pk_mul_f32 v[82:83], v[70:71], v[82:83] op_sel_hi:[0,1]
	v_pk_fma_f32 v[98:99], v[8:9], v[82:83], v[40:41]
	v_lshlrev_b32_e32 v82, 16, v59
	v_and_b32_e32 v83, 0xffff0000, v59
	v_pk_mul_f32 v[70:71], v[70:71], v[82:83] op_sel_hi:[0,1]
	v_cvt_pk_bf16_f32 v82, v86, v87
	v_pk_mul_f32 v[86:87], v[86:87], v[86:87]
	v_cvt_pk_bf16_f32 v83, v88, v89
	v_pk_mul_f32 v[88:89], v[88:89], v[88:89]
	v_add_f32_e32 v81, v86, v87
	v_add_f32_e32 v81, v88, v81
	v_cvt_pk_bf16_f32 v84, v90, v91
	v_pk_mul_f32 v[90:91], v[90:91], v[90:91]
	v_add_f32_e32 v81, v89, v81
	v_add_f32_e32 v81, v90, v81
	v_cvt_pk_bf16_f32 v85, v92, v93
	v_pk_mul_f32 v[92:93], v[92:93], v[92:93]
	v_add_f32_e32 v81, v91, v81
	v_add_f32_e32 v81, v92, v81
	global_store_dwordx4 v[100:101], v[82:85], off
	v_add_f32_e32 v81, v93, v81
	v_pk_fma_f32 v[70:71], v[10:11], v[70:71], v[42:43]
	v_cvt_pk_bf16_f32 v82, v94, v95
	v_pk_mul_f32 v[94:95], v[94:95], v[94:95]
	v_cvt_pk_bf16_f32 v83, v96, v97
	v_add_f32_e32 v81, v94, v81
	v_pk_mul_f32 v[96:97], v[96:97], v[96:97]
	v_add_f32_e32 v81, v95, v81
	v_add_f32_e32 v81, v96, v81
	v_cvt_pk_bf16_f32 v84, v98, v99
	v_pk_mul_f32 v[98:99], v[98:99], v[98:99]
	v_add_f32_e32 v81, v97, v81
	v_add_f32_e32 v81, v98, v81
	v_cvt_pk_bf16_f32 v85, v70, v71
	v_pk_mul_f32 v[70:71], v[70:71], v[70:71]
	v_add_f32_e32 v81, v99, v81
	v_add_f32_e32 v70, v70, v81
	v_add_f32_e32 v70, v71, v70
	ds_bpermute_b32 v71, v74, v70
	global_store_dwordx4 v[100:101], v[82:85], off offset:1024
	s_waitcnt lgkmcnt(0)
	v_add_f32_e32 v70, v70, v71
	ds_bpermute_b32 v71, v75, v70
	s_waitcnt lgkmcnt(0)
	v_add_f32_e32 v70, v70, v71
	ds_bpermute_b32 v71, v76, v70
	s_waitcnt lgkmcnt(0)
	v_add_f32_e32 v70, v70, v71
	ds_bpermute_b32 v71, v77, v70
	s_waitcnt lgkmcnt(0)
	v_add_f32_e32 v70, v70, v71
	ds_bpermute_b32 v71, v78, v70
	s_waitcnt lgkmcnt(0)
	v_add_f32_e32 v70, v70, v71
	ds_bpermute_b32 v71, v79, v70
	s_and_saveexec_b64 s[6:7], s[8:9]
	s_cbranch_execz .LBB0_717
	s_waitcnt lgkmcnt(0)
	v_add_f32_e32 v70, v70, v71
	v_fmamk_f32 v70, v70, 0x3a800000, v156
	v_mul_f32_e32 v71, 0x4b800000, v70
	v_cmp_gt_f32_e64 s[10:11], s28, v70
	s_nop 1
	v_cndmask_b32_e64 v70, v70, v71, s[10:11]
	v_rsq_f32_e32 v70, v70
	s_nop 0
	v_mul_f32_e32 v71, 0x45800000, v70
	v_cndmask_b32_e64 v81, v70, v71, s[10:11]
	v_lshl_add_u64 v[70:71], v[68:69], 2, s[38:39]
	global_store_dword v[70:71], v81, off
	s_branch .LBB0_717

.LBB0_942:
	v_readlane_b32 s4, v255, 15
	v_readlane_b32 s5, v255, 16
	v_mov_b32_e32 v0, v157
	s_andn2_b64 vcc, exec, s[4:5]
	s_waitcnt lgkmcnt(0)
	s_cbranch_vccnz .LBB0_1005
	s_load_dword s4, s[34:35], 0x0
	v_ashrrev_i32_e32 v120, 3, v0
	v_ashrrev_i32_e32 v121, 31, v120
	v_and_b32_e32 v1, 7, v0
	v_lshlrev_b32_e32 v128, 4, v1
	s_waitcnt lgkmcnt(0)
	s_lshr_b32 s83, s4, 3
	v_readlane_b32 s4, v255, 27
	v_readlane_b32 s5, v255, 28
	v_readlane_b32 s6, v255, 19
	v_readlane_b32 s8, v255, 5
	v_lshl_add_u64 v[6:7], v[120:121], 0, s[4:5]
	v_lshlrev_b64 v[6:7], 13, v[6:7]
	v_lshl_add_u64 v[6:7], s[26:27], 0, v[6:7]
	v_lshl_add_u64 v[6:7], v[6:7], 0, v[128:129]
	s_lshl_b32 s4, s6, 1
	s_mov_b32 s5, s36
	v_lshl_add_u64 v[6:7], v[6:7], 0, s[4:5]
	v_readlane_b32 s4, v255, 31
	v_readlane_b32 s5, v255, 32
	v_readlane_b32 s9, v255, 6
	global_load_dwordx4 v[96:99], v[6:7], off offset:384
	global_load_dwordx4 v[100:103], v[6:7], off offset:256
	v_lshl_add_u64 v[8:9], v[120:121], 0, s[4:5]
	v_lshlrev_b64 v[8:9], 11, v[8:9]
	v_lshl_add_u64 v[8:9], s[8:9], 0, v[8:9]
	v_readlane_b32 s8, v255, 23
	v_lshl_add_u64 v[8:9], v[8:9], 0, v[128:129]
	v_readlane_b32 s9, v255, 24
	s_waitcnt vmcnt(7)
	v_ashrrev_i32_e32 v17, 6, v0
	v_lshlrev_b32_e32 v122, 5, v17
	v_lshl_add_u64 v[10:11], v[8:9], 0, s[8:9]
	v_readlane_b32 s8, v255, 17
	v_readlane_b32 s9, v255, 18
	v_and_b32_e32 v125, 31, v0
	v_bfe_u32 v16, v0, 5, 1
	v_lshl_add_u64 v[12:13], v[8:9], 0, s[8:9]
	v_readlane_b32 s8, v255, 25
	v_readlane_b32 s9, v255, 26
	global_load_dwordx4 v[104:107], v[10:11], off
	global_load_dwordx4 v[88:91], v[12:13], off
	v_lshl_add_u64 v[10:11], v[8:9], 0, s[8:9]
	v_readlane_b32 s8, v255, 21
	v_readlane_b32 s9, v255, 22
	global_load_dwordx4 v[84:87], v[6:7], off offset:128
	global_load_dwordx4 v[92:95], v[6:7], off
	v_lshl_add_u64 v[6:7], v[8:9], 0, s[8:9]
	global_load_dwordx4 v[108:111], v[10:11], off
	global_load_dwordx4 v[80:83], v[6:7], off
	v_add_u32_e32 v6, s6, v122
	v_or_b32_e32 v6, v6, v125
	v_ashrrev_i32_e32 v7, 31, v6
	v_lshl_add_u64 v[6:7], v[6:7], 0, s[4:5]
	v_readlane_b32 s4, v255, 33
	v_lshlrev_b64 v[6:7], 11, v[6:7]
	v_readlane_b32 s5, v255, 34
	v_lshlrev_b32_e32 v8, 4, v16
	v_mov_b32_e32 v9, v129
	v_lshl_add_u64 v[6:7], s[4:5], 0, v[6:7]
	v_lshl_add_u64 v[6:7], v[6:7], 0, v[8:9]
	global_load_dwordx4 v[64:67], v[6:7], off offset:96
	global_load_dwordx4 v[68:71], v[6:7], off offset:64
	global_load_dwordx4 v[72:75], v[6:7], off offset:32
	global_load_dwordx4 v[76:79], v[6:7], off
	v_lshrrev_b32_e32 v3, 4, v0
	v_lshlrev_b32_e32 v2, 7, v120
	v_bitop3_b32 v4, v3, v0, 7 bitop3:0x28
	v_lshl_or_b32 v127, v4, 4, v2
	v_and_b32_e32 v4, 6, v0
	v_bitop3_b32 v3, v3, v4, 7 bitop3:0x6c
	v_lshlrev_b32_e32 v4, 3, v0
	v_lshlrev_b32_e32 v3, 4, v3
	v_and_b32_e32 v4, 8, v4
	v_or3_b32 v131, v3, v2, v4
	v_add_u32_e32 v3, 0x2000, v131
	v_lshrrev_b32_e32 v5, 1, v0
	v_bfe_u32 v14, v0, 1, 3
	v_xor_b32_e32 v158, 16, v3
	v_bitop3_b32 v3, v16, v5, 7 bitop3:0x78
	v_lshlrev_b32_e32 v163, 4, v3
	v_bitop3_b32 v3, v16, v14, 2 bitop3:0x36
	v_and_b32_e32 v15, 63, v0
	v_lshlrev_b32_e32 v2, 3, v1
	v_lshlrev_b32_e32 v164, 4, v3
	v_bitop3_b32 v3, v16, v14, 4 bitop3:0x36
	v_bfe_u32 v124, v0, 3, 3
	v_lshlrev_b32_e32 v1, 1, v1
	v_cmp_eq_u32_e64 s[8:9], 0, v15
	v_cmp_gt_u32_e64 s[10:11], 32, v15
	v_lshlrev_b32_e32 v165, 4, v3
	v_bitop3_b32 v3, v16, v14, 6 bitop3:0x36
	v_and_b32_e32 v6, 15, v0
	v_or_b32_e32 v14, 1, v1
	v_xor_b32_e32 v15, v124, v1
	v_or_b32_e32 v132, 24, v124
	v_lshlrev_b32_e32 v4, 3, v16
	v_ashrrev_i32_e32 v159, 7, v0
	v_lshl_add_u32 v160, v17, 2, v153
	v_lshlrev_b32_e32 v162, 2, v16
	v_lshlrev_b32_e32 v166, 4, v3
	v_lshlrev_b32_e32 v3, 13, v17
	v_lshlrev_b32_e32 v5, 8, v0
	s_movk_i32 s4, 0x1f00
	v_bitop3_b32 v7, v16, v0, 15 bitop3:0x78
	v_bitop3_b32 v8, v16, v6, 2 bitop3:0x36
	v_bitop3_b32 v9, v16, v6, 4 bitop3:0x36
	v_bitop3_b32 v10, v16, v6, 6 bitop3:0x36
	v_bitop3_b32 v11, v16, v6, 8 bitop3:0x36
	v_bitop3_b32 v12, v16, v6, 10 bitop3:0x36
	v_bitop3_b32 v13, v16, v6, 12 bitop3:0x36
	v_bitop3_b32 v6, v16, v6, 14 bitop3:0x36
	v_lshlrev_b32_e32 v168, 4, v15
	v_bitop3_b32 v15, v1, v124, 1 bitop3:0x36
	v_or_b32_e32 v126, 8, v124
	v_bitop3_b32 v16, v124, v1, 8 bitop3:0x36
	v_bitop3_b32 v17, v124, v14, 8 bitop3:0x36
	v_or_b32_e32 v130, 16, v124
	v_bitop3_b32 v1, v132, v1, 15 bitop3:0x6c
	v_bitop3_b32 v14, v132, v14, 15 bitop3:0x6c
	v_lshlrev_b32_e32 v0, 4, v0
	v_and_or_b32 v5, v5, s4, v3
	v_lshlrev_b32_e32 v7, 4, v7
	v_lshlrev_b32_e32 v8, 4, v8
	v_lshlrev_b32_e32 v9, 4, v9
	v_lshlrev_b32_e32 v10, 4, v10
	v_lshlrev_b32_e32 v11, 4, v11
	v_lshlrev_b32_e32 v12, 4, v12
	v_lshlrev_b32_e32 v13, 4, v13
	v_lshlrev_b32_e32 v6, 4, v6
	v_lshl_or_b32 v167, v124, 8, v3
	v_lshlrev_b32_e32 v169, 4, v15
	v_lshl_or_b32 v15, v126, 8, v3
	v_lshlrev_b32_e32 v16, 4, v16
	v_lshlrev_b32_e32 v17, 4, v17
	v_lshl_or_b32 v170, v130, 8, v3
	v_lshl_or_b32 v3, v132, 8, v3
	v_lshlrev_b32_e32 v1, 4, v1
	v_lshlrev_b32_e32 v14, 4, v14
	v_lshl_add_u64 v[134:135], s[26:27], 0, v[128:129]
	v_and_b32_e32 v128, 0x70, v0
	v_lshlrev_b32_e32 v171, 6, v159
	v_or_b32_e32 v133, v122, v125
	v_lshlrev_b32_e32 v161, 7, v125
	v_ashrrev_i32_e32 v123, 31, v122
	v_lshl_add_u64 v[136:137], s[20:21], 0, v[128:129]
	v_or_b32_e32 v173, v171, v162
	v_lshlrev_b32_e32 v174, 14, v159
	v_lshlrev_b32_e32 v128, 1, v2
	v_lshlrev_b32_e32 v138, 1, v4
	v_add_u32_e32 v175, v5, v7
	v_add_u32_e32 v176, v5, v8
	v_add_u32_e32 v177, v5, v9
	v_add_u32_e32 v178, v5, v10
	v_add_u32_e32 v179, v5, v11
	v_add_u32_e32 v180, v5, v12
	v_add_u32_e32 v181, v5, v13
	v_add_u32_e32 v182, v5, v6
	v_add_u32_e32 v183, v15, v16
	v_add_u32_e32 v184, v15, v17
	v_add_u32_e32 v185, v3, v1
	v_add_u32_e32 v186, v3, v14
	v_readlane_b32 s66, v255, 7
	s_waitcnt vmcnt(0)
	s_branch .LBB0_945

.LBB0_960:
	v_lshlrev_b32_e32 v1, 14, v32
	v_lshlrev_b32_e32 v0, 6, v32
	v_and_or_b32 v1, v1, s80, v161
	v_or_b32_e32 v2, 1, v0
	v_add_u32_e32 v146, v1, v163
	v_cmp_lt_i32_e32 vcc, v2, v139
	ds_read_b128 v[2:5], v146
	s_mov_b32 s37, s36
	s_mov_b32 s38, s36
	s_mov_b32 s39, s36
	s_mov_b32 s40, s36
	s_mov_b32 s41, s36
	s_waitcnt lgkmcnt(0)
	v_mfma_f32_32x32x16_bf16 v[48:63], v[2:5], v[76:79], 0
	s_mov_b32 s42, s36
	s_mov_b32 s43, s36
	s_mov_b32 s44, s36
	s_mov_b32 s45, s36
	s_mov_b32 s46, s36
	s_mov_b32 s47, s36
	s_mov_b32 s48, s36
	s_mov_b32 s49, s36
	s_mov_b32 s50, s36
	s_mov_b32 s51, s36
	v_mov_b64_e32 v[32:33], s[36:37]
	v_mov_b64_e32 v[34:35], s[38:39]
	v_mov_b64_e32 v[36:37], s[40:41]
	v_mov_b64_e32 v[38:39], s[42:43]
	v_mov_b64_e32 v[40:41], s[44:45]
	v_mov_b64_e32 v[42:43], s[46:47]
	v_mov_b64_e32 v[44:45], s[48:49]
	v_mov_b64_e32 v[46:47], s[50:51]
	s_and_saveexec_b64 s[6:7], vcc
	s_cbranch_execz .LBB0_962
	ds_read_b128 v[2:5], v146 offset:4096
	s_waitcnt lgkmcnt(0)
	v_mfma_f32_32x32x16_bf16 v[32:47], v[2:5], v[76:79], 0

.LBB0_985:
	v_add_u32_e32 v32, s28, v174
	v_add_u32_e32 v32, 0x4000, v32
	v_and_or_b32 v145, v32, s80, v161
	v_add_u32_e32 v190, v145, v163
	v_add_u32_e32 v191, v145, v164
	v_add_u32_e32 v189, v145, v165
	v_add_u32_e32 v188, v145, v166
	ds_read_b128 v[212:215], v190
	ds_read_b128 v[216:219], v191
	ds_read_b128 v[220:223], v189
	ds_read_b128 v[224:227], v188
	ds_read_b128 v[228:231], v190 offset:4096
	ds_read_b128 v[232:235], v191 offset:4096
	ds_read_b128 v[236:239], v189 offset:4096
	ds_read_b128 v[240:243], v188 offset:4096
	v_add_u32_e32 v144, s86, v171
	v_add_u32_e32 v33, 0x41, v144
	s_mov_b32 s37, s36
	v_cmp_lt_i32_e32 vcc, v33, v139
	s_mov_b32 s38, s36
	s_mov_b32 s39, s36
	s_mov_b32 s40, s36
	s_mov_b32 s41, s36
	s_mov_b32 s42, s36
	s_mov_b32 s43, s36
	s_mov_b32 s44, s36
	s_mov_b32 s45, s36
	s_mov_b32 s46, s36
	s_mov_b32 s47, s36
	s_mov_b32 s48, s36
	s_mov_b32 s49, s36
	s_mov_b32 s50, s36
	s_mov_b32 s51, s36
	s_waitcnt vmcnt(0) lgkmcnt(7)
	v_mfma_f32_32x32x16_bf16 v[48:63], v[212:215], v[76:79], 0
	s_waitcnt lgkmcnt(6)
	v_mfma_f32_32x32x16_bf16 v[48:63], v[216:219], v[72:75], v[48:63]
	s_waitcnt lgkmcnt(5)
	v_mfma_f32_32x32x16_bf16 v[48:63], v[220:223], v[68:71], v[48:63]
	s_waitcnt lgkmcnt(4)
	v_mfma_f32_32x32x16_bf16 v[48:63], v[224:227], v[64:67], v[48:63]
	v_mov_b64_e32 v[32:33], s[36:37]
	v_mov_b64_e32 v[34:35], s[38:39]
	v_mov_b64_e32 v[36:37], s[40:41]
	v_mov_b64_e32 v[38:39], s[42:43]
	v_mov_b64_e32 v[40:41], s[44:45]
	v_mov_b64_e32 v[42:43], s[46:47]
	v_mov_b64_e32 v[44:45], s[48:49]
	v_mov_b64_e32 v[46:47], s[50:51]
	s_and_saveexec_b64 s[6:7], vcc
	s_cbranch_execz .LBB0_993
	s_waitcnt lgkmcnt(3)
	v_mfma_f32_32x32x16_bf16 v[32:47], v[228:231], v[76:79], 0
	s_waitcnt lgkmcnt(2)
	v_mfma_f32_32x32x16_bf16 v[32:47], v[232:235], v[72:75], v[32:47]
	s_waitcnt lgkmcnt(1)
	v_mfma_f32_32x32x16_bf16 v[32:47], v[236:239], v[68:71], v[32:47]
	s_waitcnt lgkmcnt(0)
	v_mfma_f32_32x32x16_bf16 v[32:47], v[240:243], v[64:67], v[32:47]
.LBB0_993:
	s_or_b64 exec, exec, s[6:7]
	ds_read_b128 v[212:215], v189 offset:8192
	ds_read_b128 v[216:219], v189 offset:12288
	ds_read_b128 v[220:223], v188 offset:8192
	ds_read_b128 v[224:227], v188 offset:12288
	ds_read_b128 v[228:231], v190 offset:8192
	ds_read_b128 v[232:235], v190 offset:12288
	ds_read_b128 v[236:239], v191 offset:8192
	ds_read_b128 v[240:243], v191 offset:12288
	v_add_u32_e32 v144, 0x7f, v144
	v_add_u32_e32 v192, s86, v173
	v_cmp_lt_i32_e64 s[14:15], v144, v139
	s_mov_b64 s[6:7], 0
	s_and_saveexec_b64 s[38:39], vcc
	s_cbranch_execz .LBB0_995
	s_mov_b32 s99, 0x42fc0000
	s_cmp_eq_u64 s[14:15], exec
	s_cbranch_scc1 .Lsb_nmA
	s_nop 4
	v_min_f32_e64 v32, -v32, s99
	v_exp_f32_e32 v32, v32
	v_min_f32_e64 v33, -v33, s99
	v_exp_f32_e32 v33, v33
	v_add_f32_e32 v144, 1.0, v32
	v_rcp_f32_e32 v145, v144
	v_add_u32_e32 v144, 0x60, v192
	v_cmp_lt_i32_e64 s[18:19], v144, v187
	v_add_f32_e32 v144, 1.0, v33
	v_rcp_f32_e32 v146, v144
	v_mul_f32_e32 v32, v32, v145
	s_or_b64 s[18:19], s[14:15], s[18:19]
	v_cndmask_b32_e64 v144, 1.0, v32, s[18:19]
	v_mul_f32_e32 v32, v33, v146
	v_add_u32_e32 v33, 0x61, v192
	v_cndmask_b32_e64 v193, 0, v145, s[18:19]
	v_cmp_lt_i32_e64 s[18:19], v33, v187
	v_min_f32_e64 v33, -v34, s99
	v_exp_f32_e32 v33, v33
	v_min_f32_e64 v35, -v35, s99
	v_exp_f32_e32 v35, v35
	v_add_f32_e32 v34, 1.0, v33
	v_rcp_f32_e32 v34, v34
	s_or_b64 s[18:19], s[14:15], s[18:19]
	v_add_u32_e32 v145, 0x62, v192
	v_cndmask_b32_e64 v32, 1.0, v32, s[18:19]
	v_cndmask_b32_e64 v194, 0, v146, s[18:19]
	v_cmp_lt_i32_e64 s[18:19], v145, v187
	v_add_f32_e32 v145, 1.0, v35
	v_rcp_f32_e32 v145, v145
	s_or_b64 s[18:19], s[14:15], s[18:19]
	v_mul_f32_e32 v33, v33, v34
	v_cndmask_b32_e64 v195, 0, v34, s[18:19]
	v_add_u32_e32 v34, 0x63, v192
	v_cndmask_b32_e64 v146, 1.0, v33, s[18:19]
	v_cmp_lt_i32_e64 s[18:19], v34, v187
	v_min_f32_e64 v34, -v36, s99
	v_min_f32_e64 v36, -v37, s99
	v_mul_f32_e32 v33, v35, v145
	v_exp_f32_e32 v35, v34
	v_exp_f32_e32 v36, v36
	s_or_b64 s[18:19], s[14:15], s[18:19]
	v_add_u32_e32 v37, 0x68, v192
	v_cndmask_b32_e64 v34, 1.0, v33, s[18:19]
	v_cndmask_b32_e64 v196, 0, v145, s[18:19]
	v_add_f32_e32 v33, 1.0, v35
	v_cmp_lt_i32_e64 s[18:19], v37, v187
	v_add_f32_e32 v37, 1.0, v36
	v_rcp_f32_e32 v33, v33
	v_rcp_f32_e32 v37, v37
	s_or_b64 s[18:19], s[14:15], s[18:19]
	v_mul_f32_e32 v35, v35, v33
	v_cndmask_b32_e64 v197, 0, v33, s[18:19]
	v_mul_f32_e32 v33, v36, v37
	v_add_u32_e32 v36, 0x69, v192
	v_cndmask_b32_e64 v35, 1.0, v35, s[18:19]
	v_cmp_lt_i32_e64 s[18:19], v36, v187
	v_min_f32_e64 v36, -v38, s99
	s_or_b64 s[18:19], s[14:15], s[18:19]
	v_exp_f32_e32 v36, v36
	v_cndmask_b32_e64 v199, 0, v37, s[18:19]
	v_min_f32_e64 v37, -v39, s99
	v_exp_f32_e32 v37, v37
	v_cndmask_b32_e64 v198, 1.0, v33, s[18:19]
	v_add_f32_e32 v33, 1.0, v36
	v_rcp_f32_e32 v33, v33
	v_add_u32_e32 v38, 0x6a, v192
	v_cmp_lt_i32_e64 s[18:19], v38, v187
	v_add_f32_e32 v38, 1.0, v37
	v_rcp_f32_e32 v38, v38
	v_mul_f32_e32 v36, v36, v33
	s_or_b64 s[18:19], s[14:15], s[18:19]
	v_cndmask_b32_e64 v200, 1.0, v36, s[18:19]
	v_add_u32_e32 v36, 0x6b, v192
	v_cndmask_b32_e64 v201, 0, v33, s[18:19]
	v_mul_f32_e32 v33, v37, v38
	v_cmp_lt_i32_e64 s[18:19], v36, v187
	v_min_f32_e64 v36, -v40, s99
	v_min_f32_e64 v37, -v41, s99
	v_exp_f32_e32 v36, v36
	v_exp_f32_e32 v37, v37
	s_or_b64 s[18:19], s[14:15], s[18:19]
	v_cndmask_b32_e64 v203, 0, v38, s[18:19]
	v_add_u32_e32 v38, 0x70, v192
	v_cndmask_b32_e64 v202, 1.0, v33, s[18:19]
	v_add_f32_e32 v33, 1.0, v36
	v_cmp_lt_i32_e64 s[18:19], v38, v187
	v_add_f32_e32 v38, 1.0, v37
	v_rcp_f32_e32 v33, v33
	v_rcp_f32_e32 v38, v38
	s_or_b64 s[18:19], s[14:15], s[18:19]
	v_min_f32_e64 v41, -v43, s99
	v_mul_f32_e32 v36, v36, v33
	v_cndmask_b32_e64 v39, 0, v33, s[18:19]
	v_mul_f32_e32 v33, v37, v38
	v_add_u32_e32 v37, 0x71, v192
	v_cndmask_b32_e64 v36, 1.0, v36, s[18:19]
	v_cmp_lt_i32_e64 s[18:19], v37, v187
	v_min_f32_e64 v37, -v42, s99
	v_exp_f32_e32 v37, v37
	v_exp_f32_e32 v41, v41
	s_or_b64 s[18:19], s[14:15], s[18:19]
	v_add_u32_e32 v42, 0x72, v192
	v_cndmask_b32_e64 v40, 1.0, v33, s[18:19]
	v_cndmask_b32_e64 v38, 0, v38, s[18:19]
	v_add_f32_e32 v33, 1.0, v37
	v_cmp_lt_i32_e64 s[18:19], v42, v187
	v_add_f32_e32 v42, 1.0, v41
	v_rcp_f32_e32 v33, v33
	v_rcp_f32_e32 v42, v42
	s_or_b64 s[18:19], s[14:15], s[18:19]
	v_min_f32_e64 v43, -v45, s99
	v_mul_f32_e32 v37, v37, v33
	v_cndmask_b32_e64 v204, 0, v33, s[18:19]
	v_mul_f32_e32 v33, v41, v42
	v_add_u32_e32 v41, 0x73, v192
	v_cndmask_b32_e64 v37, 1.0, v37, s[18:19]
	v_cmp_lt_i32_e64 s[18:19], v41, v187
	v_min_f32_e64 v41, -v44, s99
	v_exp_f32_e32 v41, v41
	v_exp_f32_e32 v43, v43
	s_or_b64 s[18:19], s[14:15], s[18:19]
	v_add_u32_e32 v44, 0x78, v192
	v_cndmask_b32_e64 v205, 1.0, v33, s[18:19]
	v_cndmask_b32_e64 v42, 0, v42, s[18:19]
	v_add_f32_e32 v33, 1.0, v41
	v_cmp_lt_i32_e64 s[18:19], v44, v187
	v_add_f32_e32 v44, 1.0, v43
	v_rcp_f32_e32 v33, v33
	v_rcp_f32_e32 v44, v44
	s_or_b64 s[18:19], s[14:15], s[18:19]
	v_min_f32_e64 v45, -v47, s99
	v_mul_f32_e32 v41, v41, v33
	v_cndmask_b32_e64 v206, 0, v33, s[18:19]
	v_mul_f32_e32 v33, v43, v44
	v_add_u32_e32 v43, 0x79, v192
	v_cndmask_b32_e64 v41, 1.0, v41, s[18:19]
	v_cmp_lt_i32_e64 s[18:19], v43, v187
	v_min_f32_e64 v43, -v46, s99
	v_exp_f32_e32 v43, v43
	v_exp_f32_e32 v45, v45
	s_or_b64 s[18:19], s[14:15], s[18:19]
	v_add_u32_e32 v46, 0x7a, v192
	v_cndmask_b32_e64 v207, 1.0, v33, s[18:19]
	v_cndmask_b32_e64 v44, 0, v44, s[18:19]
	v_add_f32_e32 v33, 1.0, v43
	v_cmp_lt_i32_e64 s[18:19], v46, v187
	v_add_f32_e32 v46, 1.0, v45
	v_rcp_f32_e32 v33, v33
	v_rcp_f32_e32 v46, v46
	s_or_b64 s[18:19], s[14:15], s[18:19]
	v_and_b32_e32 v47, 64, v172
	v_mul_f32_e32 v43, v43, v33
	v_cndmask_b32_e64 v208, 0, v33, s[18:19]
	v_mul_f32_e32 v33, v45, v46
	v_add_u32_e32 v45, 0x7b, v192
	v_cndmask_b32_e64 v43, 1.0, v43, s[18:19]
	v_cmp_lt_i32_e64 s[18:19], v45, v187
	s_or_b64 s[18:19], s[14:15], s[18:19]
	v_add_u32_e32 v47, 64, v47
	v_cndmask_b32_e64 v45, 1.0, v33, s[18:19]
	v_xor_b32_e32 v33, 32, v172
	v_cndmask_b32_e64 v46, 0, v46, s[18:19]
	v_cmp_lt_i32_e64 s[18:19], v33, v47
	v_mul_f32_e32 v36, v36, v40
	v_mul_f32_e32 v47, v37, v205
	v_cndmask_b32_e64 v33, v172, v33, s[18:19]
	v_lshlrev_b32_e32 v209, 2, v33
	v_mul_f32_e32 v33, v35, v198
	v_mul_f32_e32 v35, v200, v202
	v_mul_f32_e32 v145, v33, v35
	v_mul_f32_e32 v35, v41, v207
	v_mul_f32_e32 v41, v43, v45
	v_mul_f32_e32 v35, v35, v41

.LBB0_998:
	v_cvt_pk_bf16_f32 v32, v32, v33
	v_cvt_pk_bf16_f32 v33, v34, v35
	v_cvt_pk_bf16_f32 v34, v36, v37
	v_cvt_pk_bf16_f32 v36, v40, v41
	v_cvt_pk_bf16_f32 v37, v42, v43
	v_cvt_pk_bf16_f32 v35, v38, v39
	v_cvt_pk_bf16_f32 v38, v44, v45
	v_cvt_pk_bf16_f32 v39, v46, v47
	s_waitcnt lgkmcnt(0)
	s_nop 0
	v_mfma_f32_32x32x16_bf16 v[0:15], v[212:215], v[32:35], v[0:15]
	v_mfma_f32_32x32x16_bf16 v[16:31], v[216:219], v[32:35], v[16:31]
	v_mfma_f32_32x32x16_bf16 v[0:15], v[220:223], v[36:39], v[0:15]
	v_mfma_f32_32x32x16_bf16 v[16:31], v[224:227], v[36:39], v[16:31]

.LBB0_1003:
	v_cvt_pk_bf16_f32 v48, v48, v49
	v_cvt_pk_bf16_f32 v49, v50, v51
	v_cvt_pk_bf16_f32 v50, v52, v53
	v_cvt_pk_bf16_f32 v52, v56, v57
	v_cvt_pk_bf16_f32 v53, v58, v59
	v_cvt_pk_bf16_f32 v51, v54, v55
	v_cvt_pk_bf16_f32 v54, v60, v61
	v_cvt_pk_bf16_f32 v55, v62, v63
	s_waitcnt lgkmcnt(0)
	s_nop 0
	v_mfma_f32_32x32x16_bf16 v[0:15], v[228:231], v[48:51], v[0:15]
	v_mfma_f32_32x32x16_bf16 v[16:31], v[232:235], v[48:51], v[16:31]
	v_mfma_f32_32x32x16_bf16 v[0:15], v[236:239], v[52:55], v[0:15]
	v_mfma_f32_32x32x16_bf16 v[16:31], v[240:243], v[52:55], v[16:31]
	s_or_b64 exec, exec, s[14:15]
	s_and_saveexec_b64 s[14:15], vcc
	s_cbranch_execnz .LBB0_998
	s_branch .LBB0_999

.LBB0_1163:
	s_or_b64 exec, exec, s[8:9]
.LBB0_1164:
	s_or_b64 exec, exec, s[6:7]
	s_waitcnt vmcnt(0)
.Le0_p8:
	ds_bpermute_b32 v52, v56, v62
	v_lshlrev_b32_e32 v66, 16, v44
	v_and_b32_e32 v67, 0xffff0000, v44
	v_lshlrev_b32_e32 v64, 16, v36
	v_and_b32_e32 v65, 0xffff0000, v36
	s_waitcnt lgkmcnt(0)
	v_add_f32_e32 v52, v62, v52
	ds_bpermute_b32 v53, v57, v52
	v_lshlrev_b32_e32 v68, 16, v45
	v_and_b32_e32 v69, 0xffff0000, v45
	v_lshlrev_b32_e32 v70, 16, v46
	v_and_b32_e32 v71, 0xffff0000, v46
	s_waitcnt lgkmcnt(0)
	v_add_f32_e32 v52, v52, v53
	ds_bpermute_b32 v53, v58, v52
	v_lshlrev_b32_e32 v72, 16, v47
	v_and_b32_e32 v73, 0xffff0000, v47
	v_lshlrev_b32_e32 v74, 16, v40
	v_and_b32_e32 v75, 0xffff0000, v40
	s_waitcnt lgkmcnt(0)
	v_add_f32_e32 v52, v52, v53
	ds_bpermute_b32 v53, v59, v52
	v_lshlrev_b32_e32 v76, 16, v41
	v_and_b32_e32 v77, 0xffff0000, v41
	v_lshlrev_b32_e32 v78, 16, v42
	v_and_b32_e32 v79, 0xffff0000, v42
	s_waitcnt lgkmcnt(0)
	v_add_f32_e32 v52, v52, v53
	ds_bpermute_b32 v53, v60, v52
	v_lshlrev_b32_e32 v80, 16, v43
	v_and_b32_e32 v81, 0xffff0000, v43
	s_waitcnt lgkmcnt(0)
	v_add_f32_e32 v52, v52, v53
	ds_bpermute_b32 v53, v61, v52
	s_waitcnt lgkmcnt(0)
	v_add_f32_e32 v52, v52, v53
	v_fmamk_f32 v52, v52, 0x3a800000, v155
	v_cmp_gt_f32_e64 s[8:9], s69, v52
	v_mul_f32_e32 v53, 0x4b800000, v52
	s_nop 0
	v_cndmask_b32_e64 v52, v52, v53, s[8:9]
	v_rsq_f32_e32 v52, v52
	s_nop 0
	v_mul_f32_e32 v53, 0x45800000, v52
	v_cndmask_b32_e64 v52, v52, v53, s[8:9]
	v_pk_mul_f32 v[66:67], v[52:53], v[66:67] op_sel_hi:[0,1]
	v_pk_fma_f32 v[64:65], v[4:5], v[66:67], v[64:65]
	v_lshlrev_b32_e32 v66, 16, v37
	v_and_b32_e32 v67, 0xffff0000, v37
	v_pk_mul_f32 v[68:69], v[52:53], v[68:69] op_sel_hi:[0,1]
	v_pk_fma_f32 v[66:67], v[6:7], v[68:69], v[66:67]
	v_lshlrev_b32_e32 v68, 16, v38
	v_and_b32_e32 v69, 0xffff0000, v38
	v_pk_mul_f32 v[70:71], v[52:53], v[70:71] op_sel_hi:[0,1]
	v_pk_fma_f32 v[68:69], v[0:1], v[70:71], v[68:69]
	v_lshlrev_b32_e32 v70, 16, v39
	v_and_b32_e32 v71, 0xffff0000, v39
	v_pk_mul_f32 v[72:73], v[52:53], v[72:73] op_sel_hi:[0,1]
	v_pk_fma_f32 v[70:71], v[2:3], v[72:73], v[70:71]
	v_lshlrev_b32_e32 v72, 16, v32
	v_and_b32_e32 v73, 0xffff0000, v32
	v_pk_mul_f32 v[74:75], v[52:53], v[74:75] op_sel_hi:[0,1]
	v_pk_fma_f32 v[72:73], v[12:13], v[74:75], v[72:73]
	v_lshlrev_b32_e32 v74, 16, v33
	v_and_b32_e32 v75, 0xffff0000, v33
	v_pk_mul_f32 v[76:77], v[52:53], v[76:77] op_sel_hi:[0,1]
	v_pk_fma_f32 v[74:75], v[14:15], v[76:77], v[74:75]
	v_lshlrev_b32_e32 v76, 16, v34
	v_and_b32_e32 v77, 0xffff0000, v34
	v_pk_mul_f32 v[78:79], v[52:53], v[78:79] op_sel_hi:[0,1]
	v_pk_fma_f32 v[76:77], v[8:9], v[78:79], v[76:77]
	v_lshlrev_b32_e32 v78, 16, v35
	v_and_b32_e32 v79, 0xffff0000, v35
	v_pk_mul_f32 v[52:53], v[52:53], v[80:81] op_sel_hi:[0,1]
	v_pk_fma_f32 v[78:79], v[10:11], v[52:53], v[78:79]
	v_lshlrev_b64 v[52:53], 12, v[50:51]
	v_lshl_or_b32 v52, v54, 2, v52
	v_lshl_add_u64 v[52:53], s[86:87], 0, v[52:53]
	global_store_dwordx4 v[52:53], v[64:67], off
	global_store_dwordx4 v[52:53], v[68:71], off offset:16
	global_store_dwordx4 v[52:53], v[72:75], off offset:2048
	global_store_dwordx4 v[52:53], v[76:79], off offset:2064

.LBB0_1166:
	v_add_u32_e32 v50, s18, v52
	v_cmp_gt_i32_e64 s[8:9], s33, v50
	v_ashrrev_i32_e32 v51, 31, v50
	s_and_saveexec_b64 s[6:7], s[8:9]
	s_cbranch_execz .LBB0_1170
	v_lshlrev_b64 v[40:41], 11, v[50:51]
	v_lshl_or_b32 v40, v54, 1, v40
	v_lshl_add_u64 v[32:33], s[56:57], 0, v[40:41]
	v_lshl_add_u64 v[40:41], s[20:21], 0, v[40:41]
	global_load_dwordx4 v[36:39], v[32:33], off
	s_nop 0
	global_load_dwordx4 v[32:35], v[32:33], off offset:1024
	s_nop 0
	global_load_dwordx4 v[44:47], v[40:41], off
	s_nop 0
	global_load_dwordx4 v[40:43], v[40:41], off offset:1024
	v_mov_b32_e32 v62, 0
	s_and_saveexec_b64 s[10:11], vcc
	s_cbranch_execz .LBB0_1169
	v_lshlrev_b64 v[62:63], 6, v[50:51]
	v_lshl_add_u64 v[62:63], v[48:49], 0, v[62:63]
	global_load_dword v62, v[62:63], off
	s_or_b64 exec, exec, s[10:11]
	s_or_b64 exec, exec, s[6:7]
	s_waitcnt vmcnt(5)
	s_branch .Le0_p7

.Le0_p7:
	ds_bpermute_b32 v53, v56, v55
	v_lshlrev_b32_e32 v66, 16, v24
	v_and_b32_e32 v67, 0xffff0000, v24
	v_lshlrev_b32_e32 v64, 16, v16
	v_and_b32_e32 v65, 0xffff0000, v16
	s_waitcnt lgkmcnt(0)
	v_add_f32_e32 v53, v55, v53
	ds_bpermute_b32 v63, v57, v53
	v_lshlrev_b32_e32 v68, 16, v25
	v_and_b32_e32 v69, 0xffff0000, v25
	v_lshlrev_b32_e32 v70, 16, v26
	v_and_b32_e32 v71, 0xffff0000, v26
	s_waitcnt lgkmcnt(0)
	v_add_f32_e32 v53, v53, v63
	ds_bpermute_b32 v63, v58, v53
	v_lshlrev_b32_e32 v72, 16, v27
	v_and_b32_e32 v73, 0xffff0000, v27
	v_lshlrev_b32_e32 v74, 16, v28
	v_and_b32_e32 v75, 0xffff0000, v28
	s_waitcnt lgkmcnt(0)
	v_add_f32_e32 v53, v53, v63
	ds_bpermute_b32 v63, v59, v53
	v_lshlrev_b32_e32 v76, 16, v29
	v_and_b32_e32 v77, 0xffff0000, v29
	v_lshlrev_b32_e32 v80, 16, v30
	v_and_b32_e32 v81, 0xffff0000, v30
	s_waitcnt lgkmcnt(0)
	v_add_f32_e32 v53, v53, v63
	ds_bpermute_b32 v63, v60, v53
	v_lshlrev_b32_e32 v82, 16, v31
	v_and_b32_e32 v83, 0xffff0000, v31
	s_waitcnt lgkmcnt(0)
	v_add_f32_e32 v53, v53, v63
	ds_bpermute_b32 v63, v61, v53
	s_waitcnt lgkmcnt(0)
	v_add_f32_e32 v53, v53, v63
	v_fmamk_f32 v53, v53, 0x3a800000, v155
	v_cmp_gt_f32_e64 s[10:11], s69, v53
	v_mul_f32_e32 v63, 0x4b800000, v53
	s_nop 0
	v_cndmask_b32_e64 v53, v53, v63, s[10:11]
	v_rsq_f32_e32 v53, v53
	s_nop 0
	v_mul_f32_e32 v63, 0x45800000, v53
	v_cndmask_b32_e64 v78, v53, v63, s[10:11]
	v_pk_mul_f32 v[66:67], v[78:79], v[66:67] op_sel_hi:[0,1]
	v_pk_fma_f32 v[64:65], v[4:5], v[66:67], v[64:65]
	v_lshlrev_b32_e32 v66, 16, v17
	v_and_b32_e32 v67, 0xffff0000, v17
	v_pk_mul_f32 v[68:69], v[78:79], v[68:69] op_sel_hi:[0,1]
	v_pk_fma_f32 v[66:67], v[6:7], v[68:69], v[66:67]
	v_lshlrev_b32_e32 v68, 16, v18
	v_and_b32_e32 v69, 0xffff0000, v18
	v_pk_mul_f32 v[70:71], v[78:79], v[70:71] op_sel_hi:[0,1]
	v_pk_fma_f32 v[68:69], v[0:1], v[70:71], v[68:69]
	v_lshlrev_b32_e32 v70, 16, v19
	v_and_b32_e32 v71, 0xffff0000, v19
	v_pk_mul_f32 v[72:73], v[78:79], v[72:73] op_sel_hi:[0,1]
	v_pk_fma_f32 v[70:71], v[2:3], v[72:73], v[70:71]
	v_lshlrev_b32_e32 v72, 16, v20
	v_and_b32_e32 v73, 0xffff0000, v20
	v_pk_mul_f32 v[74:75], v[78:79], v[74:75] op_sel_hi:[0,1]
	v_pk_fma_f32 v[72:73], v[12:13], v[74:75], v[72:73]
	v_lshlrev_b32_e32 v74, 16, v21
	v_and_b32_e32 v75, 0xffff0000, v21
	v_pk_mul_f32 v[76:77], v[78:79], v[76:77] op_sel_hi:[0,1]
	v_pk_fma_f32 v[74:75], v[14:15], v[76:77], v[74:75]
	v_lshlrev_b32_e32 v76, 16, v22
	v_and_b32_e32 v77, 0xffff0000, v22
	v_pk_mul_f32 v[80:81], v[78:79], v[80:81] op_sel_hi:[0,1]
	v_pk_fma_f32 v[76:77], v[8:9], v[80:81], v[76:77]
	v_lshlrev_b32_e32 v80, 16, v23
	v_and_b32_e32 v81, 0xffff0000, v23
	v_pk_mul_f32 v[78:79], v[78:79], v[82:83] op_sel_hi:[0,1]
	v_ashrrev_i32_e32 v53, 31, v52
	v_pk_fma_f32 v[78:79], v[10:11], v[78:79], v[80:81]
	v_lshlrev_b64 v[80:81], 12, v[52:53]
	v_lshl_or_b32 v80, v54, 2, v80
	v_lshl_add_u64 v[80:81], s[86:87], 0, v[80:81]
	global_store_dwordx4 v[80:81], v[64:67], off
	global_store_dwordx4 v[80:81], v[68:71], off offset:16
	global_store_dwordx4 v[80:81], v[72:75], off offset:2048
	global_store_dwordx4 v[80:81], v[76:79], off offset:2064
	s_and_saveexec_b64 s[10:11], s[8:9]
	s_cbranch_execz .LBB0_1165
	v_add_u32_e32 v52, s19, v52
	v_cmp_gt_i32_e64 s[8:9], s33, v52
	s_and_saveexec_b64 s[6:7], s[8:9]
	s_cbranch_execz .LBB0_1164
	v_ashrrev_i32_e32 v53, 31, v52
	v_lshlrev_b64 v[24:25], 11, v[52:53]
	v_lshl_or_b32 v24, v54, 1, v24
	v_lshl_add_u64 v[20:21], s[56:57], 0, v[24:25]
	v_lshl_add_u64 v[28:29], s[20:21], 0, v[24:25]
	global_load_dwordx4 v[16:19], v[20:21], off
	s_nop 0
	global_load_dwordx4 v[20:23], v[20:21], off offset:1024
	s_nop 0
	global_load_dwordx4 v[24:27], v[28:29], off
	s_nop 0
	global_load_dwordx4 v[28:31], v[28:29], off offset:1024
	v_mov_b32_e32 v55, 0
	s_and_saveexec_b64 s[8:9], vcc
	s_cbranch_execz .LBB0_1163
	v_lshlrev_b64 v[52:53], 6, v[52:53]
	v_lshl_add_u64 v[52:53], v[48:49], 0, v[52:53]
	global_load_dword v55, v[52:53], off
	s_or_b64 exec, exec, s[8:9]
	s_or_b64 exec, exec, s[6:7]
	s_waitcnt vmcnt(5)
	s_branch .Le0_p8

.LBB0_1182:
	v_add_u32_e32 v52, s28, v54
	v_cmp_gt_i32_e64 s[10:11], s33, v52
	v_ashrrev_i32_e32 v53, 31, v52
	s_and_saveexec_b64 s[6:7], s[10:11]
	s_cbranch_execz .LBB0_1186
	v_lshlrev_b64 v[40:41], 11, v[52:53]
	v_lshl_or_b32 v40, v56, 1, v40
	v_lshl_add_u64 v[36:37], s[56:57], 0, v[40:41]
	v_lshl_add_u64 v[40:41], s[20:21], 0, v[40:41]
	global_load_dwordx4 v[32:35], v[36:37], off
	s_nop 0
	global_load_dwordx4 v[36:39], v[36:37], off offset:1024
	s_nop 0
	global_load_dwordx4 v[44:47], v[40:41], off
	s_nop 0
	global_load_dwordx4 v[40:43], v[40:41], off offset:1024
	v_mov_b32_e32 v64, 0
	s_and_saveexec_b64 s[12:13], vcc
	s_cbranch_execz .LBB0_1185
	v_lshlrev_b64 v[64:65], 6, v[52:53]
	v_lshl_add_u64 v[64:65], v[50:51], 0, v[64:65]
	global_load_dword v64, v[64:65], off
	s_or_b64 exec, exec, s[12:13]
	s_or_b64 exec, exec, s[6:7]
	s_waitcnt vmcnt(5) lgkmcnt(0)
	s_branch .Le0_p5

.Le0_p5:
	ds_bpermute_b32 v55, v58, v57
	v_lshlrev_b32_e32 v70, 16, v24
	v_and_b32_e32 v71, 0xffff0000, v24
	v_lshlrev_b32_e32 v68, 16, v16
	v_and_b32_e32 v69, 0xffff0000, v16
	s_waitcnt lgkmcnt(0)
	v_add_f32_e32 v55, v57, v55
	ds_bpermute_b32 v65, v59, v55
	v_lshlrev_b32_e32 v72, 16, v25
	v_and_b32_e32 v73, 0xffff0000, v25
	v_lshlrev_b32_e32 v74, 16, v26
	v_and_b32_e32 v75, 0xffff0000, v26
	s_waitcnt lgkmcnt(0)
	v_add_f32_e32 v55, v55, v65
	ds_bpermute_b32 v65, v60, v55
	v_lshlrev_b32_e32 v76, 16, v27
	v_and_b32_e32 v77, 0xffff0000, v27
	v_lshlrev_b32_e32 v78, 16, v28
	v_and_b32_e32 v79, 0xffff0000, v28
	s_waitcnt lgkmcnt(0)
	v_add_f32_e32 v55, v55, v65
	ds_bpermute_b32 v65, v61, v55
	v_lshlrev_b32_e32 v80, 16, v29
	v_and_b32_e32 v81, 0xffff0000, v29
	v_lshlrev_b32_e32 v82, 16, v30
	v_and_b32_e32 v83, 0xffff0000, v30
	s_waitcnt lgkmcnt(0)
	v_add_f32_e32 v55, v55, v65
	ds_bpermute_b32 v65, v62, v55
	v_lshlrev_b32_e32 v84, 16, v31
	v_and_b32_e32 v85, 0xffff0000, v31
	s_waitcnt lgkmcnt(0)
	v_add_f32_e32 v55, v55, v65
	ds_bpermute_b32 v65, v63, v55
	s_waitcnt lgkmcnt(0)
	v_add_f32_e32 v55, v55, v65
	v_fmamk_f32 v55, v55, 0x3a800000, v155
	v_cmp_gt_f32_e64 s[12:13], s69, v55
	v_mul_f32_e32 v65, 0x4b800000, v55
	s_nop 0
	v_cndmask_b32_e64 v55, v55, v65, s[12:13]
	v_rsq_f32_e32 v55, v55
	s_nop 0
	v_mul_f32_e32 v65, 0x45800000, v55
	v_cndmask_b32_e64 v66, v55, v65, s[12:13]
	v_pk_mul_f32 v[70:71], v[66:67], v[70:71] op_sel_hi:[0,1]
	v_pk_fma_f32 v[70:71], v[4:5], v[70:71], v[68:69]
	v_lshlrev_b32_e32 v68, 16, v17
	v_and_b32_e32 v69, 0xffff0000, v17
	v_pk_mul_f32 v[72:73], v[66:67], v[72:73] op_sel_hi:[0,1]
	v_pk_fma_f32 v[72:73], v[6:7], v[72:73], v[68:69]
	v_lshlrev_b32_e32 v68, 16, v18
	v_and_b32_e32 v69, 0xffff0000, v18
	v_pk_mul_f32 v[74:75], v[66:67], v[74:75] op_sel_hi:[0,1]
	v_pk_fma_f32 v[74:75], v[0:1], v[74:75], v[68:69]
	v_lshlrev_b32_e32 v68, 16, v19
	v_and_b32_e32 v69, 0xffff0000, v19
	v_pk_mul_f32 v[76:77], v[66:67], v[76:77] op_sel_hi:[0,1]
	v_pk_fma_f32 v[76:77], v[2:3], v[76:77], v[68:69]
	v_lshlrev_b32_e32 v68, 16, v20
	v_and_b32_e32 v69, 0xffff0000, v20
	v_pk_mul_f32 v[78:79], v[66:67], v[78:79] op_sel_hi:[0,1]
	v_pk_fma_f32 v[78:79], v[12:13], v[78:79], v[68:69]
	v_lshlrev_b32_e32 v68, 16, v21
	v_and_b32_e32 v69, 0xffff0000, v21
	v_pk_mul_f32 v[80:81], v[66:67], v[80:81] op_sel_hi:[0,1]
	v_pk_fma_f32 v[80:81], v[14:15], v[80:81], v[68:69]
	v_lshlrev_b32_e32 v68, 16, v22
	v_and_b32_e32 v69, 0xffff0000, v22
	v_pk_mul_f32 v[82:83], v[66:67], v[82:83] op_sel_hi:[0,1]
	v_pk_fma_f32 v[82:83], v[8:9], v[82:83], v[68:69]
	v_lshlrev_b32_e32 v68, 16, v23
	v_and_b32_e32 v69, 0xffff0000, v23
	v_pk_mul_f32 v[66:67], v[66:67], v[84:85] op_sel_hi:[0,1]
	v_pk_fma_f32 v[84:85], v[10:11], v[66:67], v[68:69]
	v_cvt_pk_bf16_f32 v66, v70, v71
	v_pk_mul_f32 v[70:71], v[70:71], v[70:71]
	v_cvt_pk_bf16_f32 v67, v72, v73
	v_pk_mul_f32 v[72:73], v[72:73], v[72:73]
	v_add_f32_e32 v65, v70, v71
	v_add_f32_e32 v65, v72, v65
	v_cvt_pk_bf16_f32 v68, v74, v75
	v_pk_mul_f32 v[74:75], v[74:75], v[74:75]
	v_add_f32_e32 v65, v73, v65
	v_ashrrev_i32_e32 v55, 31, v54
	v_add_f32_e32 v65, v74, v65
	v_lshlrev_b64 v[86:87], 11, v[54:55]
	v_cvt_pk_bf16_f32 v69, v76, v77
	v_pk_mul_f32 v[76:77], v[76:77], v[76:77]
	v_add_f32_e32 v65, v75, v65
	v_lshl_add_u64 v[86:87], v[48:49], 0, v[86:87]
	v_add_f32_e32 v65, v76, v65
	global_store_dwordx4 v[86:87], v[66:69], off
	v_add_f32_e32 v65, v77, v65
	s_nop 0
	v_cvt_pk_bf16_f32 v66, v78, v79
	v_pk_mul_f32 v[78:79], v[78:79], v[78:79]
	v_cvt_pk_bf16_f32 v67, v80, v81
	v_add_f32_e32 v65, v78, v65
	v_pk_mul_f32 v[80:81], v[80:81], v[80:81]
	v_add_f32_e32 v65, v79, v65
	v_add_f32_e32 v65, v80, v65
	v_cvt_pk_bf16_f32 v68, v82, v83
	v_pk_mul_f32 v[82:83], v[82:83], v[82:83]
	v_add_f32_e32 v65, v81, v65
	v_add_f32_e32 v65, v82, v65
	v_cvt_pk_bf16_f32 v69, v84, v85
	v_pk_mul_f32 v[84:85], v[84:85], v[84:85]
	v_add_f32_e32 v65, v83, v65
	v_add_f32_e32 v65, v84, v65
	v_add_f32_e32 v65, v85, v65
	global_store_dwordx4 v[86:87], v[66:69], off offset:1024
	ds_bpermute_b32 v66, v58, v65
	s_waitcnt lgkmcnt(0)
	v_add_f32_e32 v65, v65, v66
	ds_bpermute_b32 v66, v59, v65
	s_waitcnt lgkmcnt(0)
	v_add_f32_e32 v65, v65, v66
	ds_bpermute_b32 v66, v60, v65
	s_waitcnt lgkmcnt(0)
	v_add_f32_e32 v65, v65, v66
	ds_bpermute_b32 v66, v61, v65
	s_waitcnt lgkmcnt(0)
	v_add_f32_e32 v65, v65, v66
	ds_bpermute_b32 v66, v62, v65
	s_waitcnt lgkmcnt(0)
	v_add_f32_e32 v65, v65, v66
	ds_bpermute_b32 v66, v63, v65
	s_and_saveexec_b64 s[6:7], s[8:9]
	s_cbranch_execz .LBB0_1188
	s_waitcnt lgkmcnt(0)
	v_add_f32_e32 v65, v65, v66
	v_fmamk_f32 v65, v65, 0x3a800000, v155
	v_mul_f32_e32 v66, 0x4b800000, v65
	v_cmp_gt_f32_e64 s[12:13], s69, v65
	s_nop 1
	v_cndmask_b32_e64 v65, v65, v66, s[12:13]
	v_rsq_f32_e32 v65, v65
	s_nop 0
	v_mul_f32_e32 v66, 0x45800000, v65
	v_cndmask_b32_e64 v65, v65, v66, s[12:13]
	v_lshl_add_u64 v[66:67], v[54:55], 2, s[62:63]
	global_store_dword v[66:67], v65, off
.LBB0_1188:
	s_or_b64 exec, exec, s[6:7]
	s_and_saveexec_b64 s[12:13], s[10:11]
	s_cbranch_execz .LBB0_1181
	v_add_u32_e32 v54, s29, v54
	v_cmp_gt_i32_e64 s[10:11], s33, v54
	s_and_saveexec_b64 s[6:7], s[10:11]
	s_cbranch_execz .LBB0_1193
	v_ashrrev_i32_e32 v55, 31, v54
	v_lshlrev_b64 v[24:25], 11, v[54:55]
	v_lshl_or_b32 v24, v56, 1, v24
	v_lshl_add_u64 v[20:21], s[56:57], 0, v[24:25]
	v_lshl_add_u64 v[28:29], s[20:21], 0, v[24:25]
	global_load_dwordx4 v[16:19], v[20:21], off
	s_nop 0
	global_load_dwordx4 v[20:23], v[20:21], off offset:1024
	s_nop 0
	global_load_dwordx4 v[24:27], v[28:29], off
	s_nop 0
	global_load_dwordx4 v[28:31], v[28:29], off offset:1024
	v_mov_b32_e32 v57, 0
	s_and_saveexec_b64 s[10:11], vcc
	s_cbranch_execz .LBB0_1192
	v_lshlrev_b64 v[54:55], 6, v[54:55]
	v_lshl_add_u64 v[54:55], v[50:51], 0, v[54:55]
	global_load_dword v57, v[54:55], off
	s_or_b64 exec, exec, s[10:11]
	s_or_b64 exec, exec, s[6:7]
	s_waitcnt vmcnt(5)
	s_branch .Le0_p6

.Le0_p6:
	ds_bpermute_b32 v54, v58, v64
	v_lshlrev_b32_e32 v68, 16, v44
	v_and_b32_e32 v69, 0xffff0000, v44
	s_waitcnt lgkmcnt(1)
	v_lshlrev_b32_e32 v66, 16, v32
	v_and_b32_e32 v67, 0xffff0000, v32
	s_waitcnt lgkmcnt(0)
	v_add_f32_e32 v54, v64, v54
	ds_bpermute_b32 v55, v59, v54
	v_lshlrev_b64 v[84:85], 11, v[52:53]
	v_lshl_add_u64 v[84:85], v[48:49], 0, v[84:85]
	s_waitcnt lgkmcnt(0)
	v_add_f32_e32 v54, v54, v55
	ds_bpermute_b32 v55, v60, v54
	s_waitcnt lgkmcnt(0)
	v_add_f32_e32 v54, v54, v55
	ds_bpermute_b32 v55, v61, v54
	s_waitcnt lgkmcnt(0)
	v_add_f32_e32 v54, v54, v55
	ds_bpermute_b32 v55, v62, v54
	s_waitcnt lgkmcnt(0)
	v_add_f32_e32 v54, v54, v55
	ds_bpermute_b32 v55, v63, v54
	s_waitcnt lgkmcnt(0)
	v_add_f32_e32 v54, v54, v55
	v_fmamk_f32 v54, v54, 0x3a800000, v155
	v_cmp_gt_f32_e64 s[10:11], s69, v54
	v_mul_f32_e32 v55, 0x4b800000, v54
	s_nop 0
	v_cndmask_b32_e64 v54, v54, v55, s[10:11]
	v_rsq_f32_e32 v54, v54
	s_nop 0
	v_mul_f32_e32 v55, 0x45800000, v54
	v_cndmask_b32_e64 v54, v54, v55, s[10:11]
	v_pk_mul_f32 v[68:69], v[54:55], v[68:69] op_sel_hi:[0,1]
	v_pk_fma_f32 v[70:71], v[4:5], v[68:69], v[66:67]
	v_lshlrev_b32_e32 v68, 16, v45
	v_and_b32_e32 v69, 0xffff0000, v45
	v_lshlrev_b32_e32 v66, 16, v33
	v_and_b32_e32 v67, 0xffff0000, v33
	v_pk_mul_f32 v[68:69], v[54:55], v[68:69] op_sel_hi:[0,1]
	v_pk_fma_f32 v[72:73], v[6:7], v[68:69], v[66:67]
	v_lshlrev_b32_e32 v68, 16, v46
	v_and_b32_e32 v69, 0xffff0000, v46
	v_lshlrev_b32_e32 v66, 16, v34
	v_and_b32_e32 v67, 0xffff0000, v34
	v_pk_mul_f32 v[68:69], v[54:55], v[68:69] op_sel_hi:[0,1]
	v_pk_fma_f32 v[74:75], v[0:1], v[68:69], v[66:67]
	v_lshlrev_b32_e32 v68, 16, v47
	v_and_b32_e32 v69, 0xffff0000, v47
	v_lshlrev_b32_e32 v66, 16, v35
	v_and_b32_e32 v67, 0xffff0000, v35
	v_pk_mul_f32 v[68:69], v[54:55], v[68:69] op_sel_hi:[0,1]
	v_pk_fma_f32 v[76:77], v[2:3], v[68:69], v[66:67]
	v_lshlrev_b32_e32 v68, 16, v40
	v_and_b32_e32 v69, 0xffff0000, v40
	v_lshlrev_b32_e32 v66, 16, v36
	v_and_b32_e32 v67, 0xffff0000, v36
	v_pk_mul_f32 v[68:69], v[54:55], v[68:69] op_sel_hi:[0,1]
	v_pk_fma_f32 v[78:79], v[12:13], v[68:69], v[66:67]
	v_lshlrev_b32_e32 v68, 16, v41
	v_and_b32_e32 v69, 0xffff0000, v41
	v_lshlrev_b32_e32 v66, 16, v37
	v_and_b32_e32 v67, 0xffff0000, v37
	v_pk_mul_f32 v[68:69], v[54:55], v[68:69] op_sel_hi:[0,1]
	v_pk_fma_f32 v[80:81], v[14:15], v[68:69], v[66:67]
	v_lshlrev_b32_e32 v68, 16, v42
	v_and_b32_e32 v69, 0xffff0000, v42
	v_lshlrev_b32_e32 v66, 16, v38
	v_and_b32_e32 v67, 0xffff0000, v38
	v_pk_mul_f32 v[68:69], v[54:55], v[68:69] op_sel_hi:[0,1]
	v_pk_fma_f32 v[82:83], v[8:9], v[68:69], v[66:67]
	v_lshlrev_b32_e32 v68, 16, v43
	v_and_b32_e32 v69, 0xffff0000, v43
	v_lshlrev_b32_e32 v66, 16, v39
	v_and_b32_e32 v67, 0xffff0000, v39
	v_pk_mul_f32 v[54:55], v[54:55], v[68:69] op_sel_hi:[0,1]
	v_pk_fma_f32 v[54:55], v[10:11], v[54:55], v[66:67]
	v_cvt_pk_bf16_f32 v66, v70, v71
	v_pk_mul_f32 v[70:71], v[70:71], v[70:71]
	v_cvt_pk_bf16_f32 v67, v72, v73
	v_pk_mul_f32 v[72:73], v[72:73], v[72:73]
	v_add_f32_e32 v65, v70, v71
	v_add_f32_e32 v65, v72, v65
	v_cvt_pk_bf16_f32 v68, v74, v75
	v_pk_mul_f32 v[74:75], v[74:75], v[74:75]
	v_add_f32_e32 v65, v73, v65
	v_add_f32_e32 v65, v74, v65
	v_cvt_pk_bf16_f32 v69, v76, v77
	v_pk_mul_f32 v[76:77], v[76:77], v[76:77]
	v_add_f32_e32 v65, v75, v65
	v_add_f32_e32 v65, v76, v65
	global_store_dwordx4 v[84:85], v[66:69], off
	v_add_f32_e32 v65, v77, v65
	s_nop 0
	v_cvt_pk_bf16_f32 v66, v78, v79
	v_pk_mul_f32 v[78:79], v[78:79], v[78:79]
	v_cvt_pk_bf16_f32 v67, v80, v81
	v_add_f32_e32 v65, v78, v65
	v_pk_mul_f32 v[80:81], v[80:81], v[80:81]
	v_add_f32_e32 v65, v79, v65
	v_add_f32_e32 v65, v80, v65
	v_cvt_pk_bf16_f32 v68, v82, v83
	v_pk_mul_f32 v[82:83], v[82:83], v[82:83]
	v_add_f32_e32 v65, v81, v65
	v_add_f32_e32 v65, v82, v65
	v_cvt_pk_bf16_f32 v69, v54, v55
	v_pk_mul_f32 v[54:55], v[54:55], v[54:55]
	v_add_f32_e32 v65, v83, v65
	v_add_f32_e32 v54, v54, v65
	v_add_f32_e32 v54, v55, v54
	ds_bpermute_b32 v55, v58, v54
	global_store_dwordx4 v[84:85], v[66:69], off offset:1024
	s_waitcnt lgkmcnt(0)
	v_add_f32_e32 v54, v54, v55
	ds_bpermute_b32 v55, v59, v54
	s_waitcnt lgkmcnt(0)
	v_add_f32_e32 v54, v54, v55
	ds_bpermute_b32 v55, v60, v54
	s_waitcnt lgkmcnt(0)
	v_add_f32_e32 v54, v54, v55
	ds_bpermute_b32 v55, v61, v54
	s_waitcnt lgkmcnt(0)
	v_add_f32_e32 v54, v54, v55
	ds_bpermute_b32 v55, v62, v54
	s_waitcnt lgkmcnt(0)
	v_add_f32_e32 v54, v54, v55
	ds_bpermute_b32 v55, v63, v54
	s_and_saveexec_b64 s[6:7], s[8:9]
	s_cbranch_execz .LBB0_1180
	s_waitcnt lgkmcnt(0)
	v_add_f32_e32 v54, v54, v55
	v_fmamk_f32 v54, v54, 0x3a800000, v155
	v_mul_f32_e32 v55, 0x4b800000, v54
	v_cmp_gt_f32_e64 s[10:11], s69, v54
	s_nop 1
	v_cndmask_b32_e64 v54, v54, v55, s[10:11]
	v_rsq_f32_e32 v54, v54
	s_nop 0
	v_mul_f32_e32 v55, 0x45800000, v54
	v_cndmask_b32_e64 v65, v54, v55, s[10:11]
	v_lshl_add_u64 v[54:55], v[52:53], 2, s[62:63]
	global_store_dword v[54:55], v65, off
	s_branch .LBB0_1180
